# diff-attention loop unrolled by 4 ring slots: all LDS addresses are VGPR+immediate (no per-tile address VALU/SALU), shorter staging sequence; plus mem-unit prologue prefetch
# speedup vs baseline: 1.0079x; 1.0079x over previous
; __device__ __forceinline__ int opaque_tid(int wv) { int lane_; asm volatile("v_mbcnt_lo_u32_b32 %0, -1, 0\n\tv_mbcnt_hi_u32_b32 %0, -1, %0" : "=v"(lane_)); return wv * 64 + lane_; }
; #define SBAR() __builtin_amdgcn_sched_barrier(0)
; #define STAGE(t) do { const char* kt_ = Pk + (size_t)((t) * KVBLK) * (INC * 2); const int so_ = ((t) & 3) * SHM_K; \
;     GLDS(kt_ + koff, ldsA + 4 * SHM_V + so_); GLDS(kt_ + 32 * INC * 2 + koff, ldsA + 4 * SHM_V + so_ + 8192); \
;     GLDS(kt_ + voff, ldsA + so_); GLDS(kt_ + 32 * INC * 2 + voff, ldsA + so_ + 8192); } while (0)
; #define ENDI() do { asm volatile("s_waitcnt vmcnt(0)" ::: "memory"); __syncthreads(); } while (0)
; #define BIAS(P0, P1, t) bias_init(P0, P1, (float)(iposk - (t) * KVBLK), nslope2, nM2, relw + (t) * KVBLK)
; __device__ __forceinline__ void diff_unit(const DiffArgs& A, int b, int h, int qb, char* lds, int wv) {
;     ...
;     f32x16 pA0, pA1, pB0, pB1; bf16x8 pa0, pa1, pa2, pa3; const int NT = nt;
;     STAGE(0); ENDI();
;     STAGE(1);
;     BIAS(pA0, pA1, 0); qkt<4>(pA0, pA1, K_lds, qr, r32, hi, colB0);
;     ...
;     if (c == 0) {
;     ...
;         const int lp_ = opaque_tid(wv) & 63, r32p = lp_ & 31, hip = lp_ >> 5;
;         exp_half(pA0);
;         ENDI();
; #pragma unroll 1
;         for (int j = 1; j + 1 < NT; j += 2) {
;             STAGE(j + 1);
;             SBAR(); BIAS(pB0, pB1, j); qkt<4>(pB0, pB1, K_lds + SLOT(j), qr, r32p, hip, colB0);
;             exp_half(pA1); pack_p(pA0, pA1, l_reg, pa0, pa1, pa2, pa3); SBAR();
;             pv_d0(o, vb0 + SLOT(j - 1), pa0, pa1, pa2, pa3); exp_half(pB0);
;             ENDI();
;             STAGE(j + 2);
;             SBAR(); BIAS(pA0, pA1, j + 1); qkt<4>(pA0, pA1, K_lds + SLOT(j + 1), qr, r32p, hip, colB0);
;             exp_half(pB1); pack_p(pB0, pB1, l_reg, pa0, pa1, pa2, pa3); SBAR();
;             pv_d0(o, vb0 + SLOT(j), pa0, pa1, pa2, pa3); exp_half(pA0);
;             ENDI();
;         }
.Lsym_entry:
	v_mov_b32_e32 v0, 0
	v_mov_b32_e32 v1, 0
	v_mov_b32_e32 v2, 0
	v_mov_b32_e32 v3, 0
	v_mov_b32_e32 v4, 0
	v_mov_b32_e32 v5, 0
	v_mov_b32_e32 v6, 0
	v_mov_b32_e32 v7, 0
	v_mov_b32_e32 v8, 0
	v_mov_b32_e32 v9, 0
	v_mov_b32_e32 v10, 0
	v_mov_b32_e32 v11, 0
	v_mov_b32_e32 v12, 0
	v_mov_b32_e32 v13, 0
	v_mov_b32_e32 v14, 0
	v_mov_b32_e32 v15, 0
	v_mov_b32_e32 v16, 0
	v_mov_b32_e32 v17, 0
	v_mov_b32_e32 v18, 0
	v_mov_b32_e32 v19, 0
	v_mov_b32_e32 v20, 0
	v_mov_b32_e32 v21, 0
	v_mov_b32_e32 v22, 0
	v_mov_b32_e32 v23, 0
	v_mov_b32_e32 v24, 0
	v_mov_b32_e32 v25, 0
	v_mov_b32_e32 v26, 0
	v_mov_b32_e32 v27, 0
	v_mov_b32_e32 v28, 0
	v_mov_b32_e32 v29, 0
	v_mov_b32_e32 v30, 0
	v_mov_b32_e32 v31, 0
	v_mov_b32_e32 v32, 0
	v_mov_b32_e32 v33, 0
	v_mov_b32_e32 v34, 0
	v_mov_b32_e32 v35, 0
	v_mov_b32_e32 v36, 0
	v_mov_b32_e32 v37, 0
	v_mov_b32_e32 v38, 0
	v_mov_b32_e32 v39, 0
	v_mov_b32_e32 v40, 0
	v_mov_b32_e32 v41, 0
	v_mov_b32_e32 v42, 0
	v_mov_b32_e32 v43, 0
	v_mov_b32_e32 v44, 0
	v_mov_b32_e32 v45, 0
	v_mov_b32_e32 v46, 0
	v_mov_b32_e32 v47, 0
	v_mov_b32_e32 v48, 0
	v_mov_b32_e32 v49, 0
	v_mov_b32_e32 v50, 0
	v_mov_b32_e32 v51, 0
	v_mov_b32_e32 v52, 0
	v_mov_b32_e32 v53, 0
	v_mov_b32_e32 v54, 0
	v_mov_b32_e32 v55, 0
	v_mov_b32_e32 v56, 0
	v_mov_b32_e32 v57, 0
	v_mov_b32_e32 v58, 0
	v_mov_b32_e32 v59, 0
	v_mov_b32_e32 v60, 0
	v_mov_b32_e32 v61, 0
	v_mov_b32_e32 v62, 0
	v_mov_b32_e32 v63, 0
	v_mov_b32_e32 v182, 0
	v_mbcnt_lo_u32_b32 v190, -1, 0
	v_mbcnt_hi_u32_b32 v190, -1, v190
	v_and_b32_e32 v191, 31, v190
	v_lshrrev_b32_e32 v187, 5, v190
	v_lshlrev_b32_e32 v185, 4, v187
	v_or_b32_e32 v185, s52, v185
	v_and_b32_e32 v183, 15, v191
	v_lshlrev_b32_e32 v183, 4, v183
	v_xor_b32_e32 v185, v185, v183
	v_lshlrev_b32_e32 v183, 8, v191
	v_xor_b32_e32 v178, 0, v185
	v_add_u32_e32 v178, v178, v183
	v_add_u32_e32 v178, 0x10000, v178
	v_xor_b32_e32 v179, 32, v185
	v_add_u32_e32 v179, v179, v183
	v_add_u32_e32 v179, 0x10000, v179
	v_xor_b32_e32 v180, 64, v185
	v_add_u32_e32 v180, v180, v183
	v_add_u32_e32 v180, 0x10000, v180
	v_xor_b32_e32 v181, 96, v185
	v_add_u32_e32 v181, v181, v183
	v_add_u32_e32 v181, 0x10000, v181
	s_mov_b32 s54, 0
	s_add_u32 s56, s20, 0x1c1e00
	s_addc_u32 s57, s21, 0
	v_exp_f32_e32 v80, v80
	v_exp_f32_e32 v81, v81
	v_exp_f32_e32 v82, v82
	v_exp_f32_e32 v83, v83
	v_add_f32_e32 v182, v80, v182
	v_add_f32_e32 v182, v81, v182
	v_cvt_pk_bf16_f32 v128, v80, v81
	v_exp_f32_e32 v84, v84
	v_exp_f32_e32 v85, v85
	v_add_f32_e32 v182, v82, v182
	v_add_f32_e32 v182, v83, v182
	v_cvt_pk_bf16_f32 v129, v82, v83
	v_exp_f32_e32 v86, v86
	v_exp_f32_e32 v87, v87
	v_add_f32_e32 v182, v84, v182
	v_add_f32_e32 v182, v85, v182
	v_cvt_pk_bf16_f32 v130, v84, v85
	v_add_f32_e32 v182, v86, v182
	v_add_f32_e32 v182, v87, v182
	v_cvt_pk_bf16_f32 v131, v86, v87
.Lsym_loop:
	s_waitcnt vmcnt(0)
	s_barrier
	ds_read_b128 v[192:195], v178 offset:16384
	ds_read_b128 v[196:199], v178 offset:24576
	ds_read_b128 v[200:203], v179 offset:16384
	ds_read_b128 v[204:207], v179 offset:24576
	ds_read_b128 v[208:211], v180 offset:16384
	ds_read_b128 v[212:215], v180 offset:24576
	ds_read_b128 v[216:219], v181 offset:16384
	ds_read_b128 v[220:223], v181 offset:24576
	s_add_i32 s53, s54, 2
	s_cmp_le_i32 s53, s62
	s_cbranch_scc0 .Lsym_nostage_s0
	s_add_u32 s60, s56, 0x70000
	s_addc_u32 s61, s57, 0
	s_add_i32 m0, s25, 0x8000
	s_nop 0
	global_load_lds_dwordx4 v176, s[56:57]
	s_add_i32 m0, s25, 0xa000
	s_nop 0
	global_load_lds_dwordx4 v176, s[60:61]
	s_add_i32 m0, s24, 0x8000
	s_nop 0
	global_load_lds_dwordx4 v188, s[56:57]
	s_add_i32 m0, s24, 0xa000
	s_nop 0
	global_load_lds_dwordx4 v188, s[60:61]
	s_add_u32 s56, s56, 0xe0000
	s_addc_u32 s57, s57, 0

; template <int KS> __device__ __forceinline__ void pv_ks(f32x16* o, int vb, bf16x8 pa) {
;     const s16x4 l0 = tr_read<v_rd_off(0, KS, 0)>(vb), h0 = tr_read<v_rd_off(0, KS, 1)>(vb), l1 = tr_read<v_rd_off(1, KS, 0)>(vb), h1 = tr_read<v_rd_off(1, KS, 1)>(vb);
;     const s16x4 l2 = tr_read<v_rd_off(2, KS, 0)>(vb), h2 = tr_read<v_rd_off(2, KS, 1)>(vb), l3 = tr_read<v_rd_off(3, KS, 0)>(vb), h3 = tr_read<v_rd_off(3, KS, 1)>(vb);
;     ...
;     asm volatile("s_waitcnt lgkmcnt(6)" ::: "memory"); SBAR();
;     o[0] = __builtin_amdgcn_mfma_f32_32x32x16_bf16(pa, PK(l0, h0), o[0], 0, 0, 0);
;     asm volatile("s_waitcnt lgkmcnt(4)" ::: "memory"); SBAR();
;     o[1] = __builtin_amdgcn_mfma_f32_32x32x16_bf16(pa, PK(l1, h1), o[1], 0, 0, 0);
;     asm volatile("s_waitcnt lgkmcnt(2)" ::: "memory"); SBAR();
;     o[2] = __builtin_amdgcn_mfma_f32_32x32x16_bf16(pa, PK(l2, h2), o[2], 0, 0, 0);
;     asm volatile("s_waitcnt lgkmcnt(0)" ::: "memory"); SBAR();
;     o[3] = __builtin_amdgcn_mfma_f32_32x32x16_bf16(pa, PK(l3, h3), o[3], 0, 0, 0);
;     ...
; }
; __device__ __forceinline__ void pv_d0(f32x16* o, int vb, bf16x8 pa0, bf16x8 pa1, bf16x8 pa2, bf16x8 pa3) {
;     __builtin_amdgcn_s_setprio(1);
;     pv_ks<0>(o, vb, pa0); pv_ks<1>(o, vb, pa1); pv_ks<2>(o, vb, pa2); pv_ks<3>(o, vb, pa3);
;     __builtin_amdgcn_s_setprio(0);
; }
; __device__ __forceinline__ void exp_half(f32x16& p) {
; #pragma unroll
;     for (int r = 0; r < 16; ++r) p[r] = __builtin_amdgcn_exp2f(p[r]);
; }
; __device__ __forceinline__ void pack_p(const f32x16& p0, const f32x16& p1, float& l_reg, bf16x8& pa0, bf16x8& pa1, bf16x8& pa2, bf16x8& pa3) {
; __device__ __forceinline__ void diff_unit(const DiffArgs& A, int b, int h, int qb, char* lds, int wv) {
;     ...
;         for (int j = 1; j + 1 < NT; j += 2) {
;             STAGE(j + 1);
;             SBAR(); BIAS(pB0, pB1, j); qkt<4>(pB0, pB1, K_lds + SLOT(j), qr, r32p, hip, colB0);
;             exp_half(pA1); pack_p(pA0, pA1, l_reg, pa0, pa1, pa2, pa3); SBAR();
;             pv_d0(o, vb0 + SLOT(j - 1), pa0, pa1, pa2, pa3); exp_half(pB0);
;             ENDI();
;             STAGE(j + 2);
;             SBAR(); BIAS(pA0, pA1, j + 1); qkt<4>(pA0, pA1, K_lds + SLOT(j + 1), qr, r32p, hip, colB0);
;             exp_half(pB1); pack_p(pB0, pB1, l_reg, pa0, pa1, pa2, pa3); SBAR();
;             pv_d0(o, vb0 + SLOT(j), pa0, pa1, pa2, pa3); exp_half(pA0);
;             ENDI();
;         }
.Lsym_biasdone_s0:
	ds_read_b64_tr_b16 v[144:145], v252 offset:0
	ds_read_b64_tr_b16 v[146:147], v252 offset:2048
	ds_read_b64_tr_b16 v[148:149], v252 offset:512
	ds_read_b64_tr_b16 v[150:151], v252 offset:2560
	ds_read_b64_tr_b16 v[152:153], v252 offset:1024
	ds_read_b64_tr_b16 v[154:155], v252 offset:3072
	ds_read_b64_tr_b16 v[156:157], v252 offset:1536
	ds_read_b64_tr_b16 v[158:159], v252 offset:3584
	s_waitcnt lgkmcnt(6)
	v_mfma_f32_32x32x16_bf16 v[48:63], v[128:131], v[144:147], v[48:63]
	ds_read_b64_tr_b16 v[144:145], v252 offset:4096
	ds_read_b64_tr_b16 v[146:147], v252 offset:6144
	v_exp_f32_e32 v88, v88
	v_exp_f32_e32 v89, v89
	s_waitcnt lgkmcnt(6)
	v_mfma_f32_32x32x16_bf16 v[32:47], v[128:131], v[148:151], v[32:47]
	ds_read_b64_tr_b16 v[148:149], v252 offset:4608
	ds_read_b64_tr_b16 v[150:151], v252 offset:6656
	v_exp_f32_e32 v90, v90
	v_exp_f32_e32 v91, v91
	v_add_f32_e32 v182, v88, v182
	v_add_f32_e32 v182, v89, v182
	v_cvt_pk_bf16_f32 v132, v88, v89
	s_waitcnt lgkmcnt(6)
	v_mfma_f32_32x32x16_bf16 v[16:31], v[128:131], v[152:155], v[16:31]
	ds_read_b64_tr_b16 v[152:153], v252 offset:5120
	ds_read_b64_tr_b16 v[154:155], v252 offset:7168
	v_exp_f32_e32 v92, v92
	v_exp_f32_e32 v93, v93
	v_add_f32_e32 v182, v90, v182
	v_add_f32_e32 v182, v91, v182
	v_cvt_pk_bf16_f32 v133, v90, v91
	s_waitcnt lgkmcnt(6)
	v_mfma_f32_32x32x16_bf16 v[0:15], v[128:131], v[156:159], v[0:15]
	ds_read_b64_tr_b16 v[156:157], v252 offset:5632
	ds_read_b64_tr_b16 v[158:159], v252 offset:7680
	v_exp_f32_e32 v94, v94
	v_exp_f32_e32 v95, v95
	v_add_f32_e32 v182, v92, v182
	v_add_f32_e32 v182, v93, v182
	v_cvt_pk_bf16_f32 v134, v92, v93
	v_add_f32_e32 v182, v94, v182
	v_add_f32_e32 v182, v95, v182
	v_cvt_pk_bf16_f32 v135, v94, v95
	v_mfma_f32_32x32x16_bf16 v[112:127], v[192:195], v[172:175], v[112:127]
	v_mfma_f32_32x32x16_bf16 v[96:111], v[196:199], v[172:175], v[96:111]
	v_mfma_f32_32x32x16_bf16 v[112:127], v[200:203], v[168:171], v[112:127]
	v_mfma_f32_32x32x16_bf16 v[96:111], v[204:207], v[168:171], v[96:111]
	s_waitcnt lgkmcnt(6)
	v_mfma_f32_32x32x16_bf16 v[48:63], v[132:135], v[144:147], v[48:63]
	ds_read_b64_tr_b16 v[144:145], v252 offset:8192
	ds_read_b64_tr_b16 v[146:147], v252 offset:10240
	v_exp_f32_e32 v64, v64
	v_exp_f32_e32 v65, v65
	s_waitcnt lgkmcnt(6)
	v_mfma_f32_32x32x16_bf16 v[32:47], v[132:135], v[148:151], v[32:47]
	ds_read_b64_tr_b16 v[148:149], v252 offset:8704
	ds_read_b64_tr_b16 v[150:151], v252 offset:10752
	v_exp_f32_e32 v66, v66
	v_exp_f32_e32 v67, v67
	v_add_f32_e32 v182, v64, v182
	v_add_f32_e32 v182, v65, v182
	v_cvt_pk_bf16_f32 v136, v64, v65
	s_waitcnt lgkmcnt(6)
	v_mfma_f32_32x32x16_bf16 v[16:31], v[132:135], v[152:155], v[16:31]
	ds_read_b64_tr_b16 v[152:153], v252 offset:9216
	ds_read_b64_tr_b16 v[154:155], v252 offset:11264
	v_exp_f32_e32 v68, v68
	v_exp_f32_e32 v69, v69
	v_add_f32_e32 v182, v66, v182
	v_add_f32_e32 v182, v67, v182
	v_cvt_pk_bf16_f32 v137, v66, v67
	s_waitcnt lgkmcnt(6)
	v_mfma_f32_32x32x16_bf16 v[0:15], v[132:135], v[156:159], v[0:15]
	ds_read_b64_tr_b16 v[156:157], v252 offset:9728
	ds_read_b64_tr_b16 v[158:159], v252 offset:11776
	v_exp_f32_e32 v70, v70
	v_exp_f32_e32 v71, v71
	v_add_f32_e32 v182, v68, v182
	v_add_f32_e32 v182, v69, v182
	v_cvt_pk_bf16_f32 v138, v68, v69
	v_add_f32_e32 v182, v70, v182
	v_add_f32_e32 v182, v71, v182
	v_cvt_pk_bf16_f32 v139, v70, v71
	v_mfma_f32_32x32x16_bf16 v[112:127], v[208:211], v[164:167], v[112:127]
	v_mfma_f32_32x32x16_bf16 v[96:111], v[212:215], v[164:167], v[96:111]
	v_mfma_f32_32x32x16_bf16 v[112:127], v[216:219], v[160:163], v[112:127]
	v_mfma_f32_32x32x16_bf16 v[96:111], v[220:223], v[160:163], v[96:111]
	s_waitcnt lgkmcnt(6)
	v_mfma_f32_32x32x16_bf16 v[48:63], v[136:139], v[144:147], v[48:63]
	ds_read_b64_tr_b16 v[144:145], v252 offset:12288
	ds_read_b64_tr_b16 v[146:147], v252 offset:14336
	v_exp_f32_e32 v72, v72
	v_exp_f32_e32 v73, v73
	s_waitcnt lgkmcnt(6)
	v_mfma_f32_32x32x16_bf16 v[32:47], v[136:139], v[148:151], v[32:47]
	ds_read_b64_tr_b16 v[148:149], v252 offset:12800
	ds_read_b64_tr_b16 v[150:151], v252 offset:14848
	v_exp_f32_e32 v74, v74
	v_exp_f32_e32 v75, v75
	v_add_f32_e32 v182, v72, v182
	v_add_f32_e32 v182, v73, v182
	v_cvt_pk_bf16_f32 v140, v72, v73
	s_waitcnt lgkmcnt(6)
	v_mfma_f32_32x32x16_bf16 v[16:31], v[136:139], v[152:155], v[16:31]
	ds_read_b64_tr_b16 v[152:153], v252 offset:13312
	ds_read_b64_tr_b16 v[154:155], v252 offset:15360
	v_exp_f32_e32 v76, v76
	v_exp_f32_e32 v77, v77
	v_add_f32_e32 v182, v74, v182
	v_add_f32_e32 v182, v75, v182
	v_cvt_pk_bf16_f32 v141, v74, v75
	s_waitcnt lgkmcnt(6)
	v_mfma_f32_32x32x16_bf16 v[0:15], v[136:139], v[156:159], v[0:15]
	ds_read_b64_tr_b16 v[156:157], v252 offset:13824
	ds_read_b64_tr_b16 v[158:159], v252 offset:15872
	v_exp_f32_e32 v78, v78
	v_exp_f32_e32 v79, v79
	v_add_f32_e32 v182, v76, v182
	v_add_f32_e32 v182, v77, v182
	v_cvt_pk_bf16_f32 v142, v76, v77
	v_add_f32_e32 v182, v78, v182
	v_add_f32_e32 v182, v79, v182
	v_cvt_pk_bf16_f32 v143, v78, v79
	s_nop 1
	s_waitcnt lgkmcnt(6)
	v_mfma_f32_32x32x16_bf16 v[48:63], v[140:143], v[144:147], v[48:63]
	v_exp_f32_e32 v112, v112
	v_exp_f32_e32 v113, v113
	s_waitcnt lgkmcnt(4)
	v_mfma_f32_32x32x16_bf16 v[32:47], v[140:143], v[148:151], v[32:47]
	v_exp_f32_e32 v114, v114
	v_exp_f32_e32 v115, v115
	v_add_f32_e32 v182, v112, v182
	v_add_f32_e32 v182, v113, v182
	v_cvt_pk_bf16_f32 v128, v112, v113
	s_waitcnt lgkmcnt(2)
	v_mfma_f32_32x32x16_bf16 v[16:31], v[140:143], v[152:155], v[16:31]
	v_exp_f32_e32 v116, v116
	v_exp_f32_e32 v117, v117
	v_add_f32_e32 v182, v114, v182
	v_add_f32_e32 v182, v115, v182
	v_cvt_pk_bf16_f32 v129, v114, v115
	s_waitcnt lgkmcnt(0)
	v_mfma_f32_32x32x16_bf16 v[0:15], v[140:143], v[156:159], v[0:15]
	v_exp_f32_e32 v118, v118
	v_exp_f32_e32 v119, v119
	v_add_f32_e32 v182, v116, v182
	v_add_f32_e32 v182, v117, v182
	v_cvt_pk_bf16_f32 v130, v116, v117
	v_add_f32_e32 v182, v118, v182
	v_add_f32_e32 v182, v119, v182
	v_cvt_pk_bf16_f32 v131, v118, v119
	s_nop 1
	s_add_i32 s54, s54, 1
	s_cmp_ge_i32 s54, s62
	s_cbranch_scc1 .Lsym_last1
	s_waitcnt vmcnt(0)
	s_barrier
	ds_read_b128 v[192:195], v178 offset:32768
	ds_read_b128 v[196:199], v178 offset:40960
	ds_read_b128 v[200:203], v179 offset:32768
	ds_read_b128 v[204:207], v179 offset:40960
	ds_read_b128 v[208:211], v180 offset:32768
	ds_read_b128 v[212:215], v180 offset:40960
	ds_read_b128 v[216:219], v181 offset:32768
	ds_read_b128 v[220:223], v181 offset:40960
	s_add_i32 s53, s54, 2
	s_cmp_le_i32 s53, s62
	s_cbranch_scc0 .Lsym_nostage_s1
	s_add_u32 s60, s56, 0x70000
	s_addc_u32 s61, s57, 0
	s_add_i32 m0, s25, 0xc000
	s_nop 0
	global_load_lds_dwordx4 v176, s[56:57]
	s_add_i32 m0, s25, 0xe000
	s_nop 0
	global_load_lds_dwordx4 v176, s[60:61]
	s_add_i32 m0, s24, 0xc000
	s_nop 0
	global_load_lds_dwordx4 v188, s[56:57]
	s_add_i32 m0, s24, 0xe000
	s_nop 0
	global_load_lds_dwordx4 v188, s[60:61]
	s_add_u32 s56, s56, 0xe0000
	s_addc_u32 s57, s57, 0

; template <int KS> __device__ __forceinline__ void pv_ks(f32x16* o, int vb, bf16x8 pa) {
;     const s16x4 l0 = tr_read<v_rd_off(0, KS, 0)>(vb), h0 = tr_read<v_rd_off(0, KS, 1)>(vb), l1 = tr_read<v_rd_off(1, KS, 0)>(vb), h1 = tr_read<v_rd_off(1, KS, 1)>(vb);
;     const s16x4 l2 = tr_read<v_rd_off(2, KS, 0)>(vb), h2 = tr_read<v_rd_off(2, KS, 1)>(vb), l3 = tr_read<v_rd_off(3, KS, 0)>(vb), h3 = tr_read<v_rd_off(3, KS, 1)>(vb);
;     ...
;     asm volatile("s_waitcnt lgkmcnt(6)" ::: "memory"); SBAR();
;     o[0] = __builtin_amdgcn_mfma_f32_32x32x16_bf16(pa, PK(l0, h0), o[0], 0, 0, 0);
;     asm volatile("s_waitcnt lgkmcnt(4)" ::: "memory"); SBAR();
;     o[1] = __builtin_amdgcn_mfma_f32_32x32x16_bf16(pa, PK(l1, h1), o[1], 0, 0, 0);
;     asm volatile("s_waitcnt lgkmcnt(2)" ::: "memory"); SBAR();
;     o[2] = __builtin_amdgcn_mfma_f32_32x32x16_bf16(pa, PK(l2, h2), o[2], 0, 0, 0);
;     asm volatile("s_waitcnt lgkmcnt(0)" ::: "memory"); SBAR();
;     o[3] = __builtin_amdgcn_mfma_f32_32x32x16_bf16(pa, PK(l3, h3), o[3], 0, 0, 0);
;     ...
; }
; __device__ __forceinline__ void pv_d0(f32x16* o, int vb, bf16x8 pa0, bf16x8 pa1, bf16x8 pa2, bf16x8 pa3) {
;     __builtin_amdgcn_s_setprio(1);
;     pv_ks<0>(o, vb, pa0); pv_ks<1>(o, vb, pa1); pv_ks<2>(o, vb, pa2); pv_ks<3>(o, vb, pa3);
;     __builtin_amdgcn_s_setprio(0);
; }
; __device__ __forceinline__ void exp_half(f32x16& p) {
; #pragma unroll
;     for (int r = 0; r < 16; ++r) p[r] = __builtin_amdgcn_exp2f(p[r]);
; }
; __device__ __forceinline__ void pack_p(const f32x16& p0, const f32x16& p1, float& l_reg, bf16x8& pa0, bf16x8& pa1, bf16x8& pa2, bf16x8& pa3) {
;     float ps = 0;
; #pragma unroll
;     for (int r = 0; r < 16; ++r) ps += p0[r];
; #pragma unroll
;     for (int r = 0; r < 16; ++r) ps += p1[r];
;     l_reg += ps;
;     ...
;     PK4(p0, 0, pa0); PK4(p0, 8, pa1); PK4(p1, 0, pa2); PK4(p1, 8, pa3);
;     ...
; }
; template <int ND0> __device__ __forceinline__ void qkt(f32x16& p0, f32x16& p1, const char* Ks, const bf16x8* qr, int r32, int hi, int colB0) {
; #pragma unroll
;     for (int d0 = 0; d0 < ND0; ++d0) { const int cb = colB0 + (d0 * 16 + hi * 8) * 2;
;         const bf16x8 b0 = *reinterpret_cast<const bf16x8*>(Ks + KSWZ(r32, cb));
;         const bf16x8 b1 = *reinterpret_cast<const bf16x8*>(Ks + KSWZ(32 + r32, cb));
;         p0 = __builtin_amdgcn_mfma_f32_32x32x16_bf16(b0, qr[d0], p0, 0, 0, 0);
.Lsym_biasdone_s1:
	ds_read_b64_tr_b16 v[144:145], v252 offset:16384
	ds_read_b64_tr_b16 v[146:147], v252 offset:18432
	ds_read_b64_tr_b16 v[148:149], v252 offset:16896
	ds_read_b64_tr_b16 v[150:151], v252 offset:18944
	ds_read_b64_tr_b16 v[152:153], v252 offset:17408
	ds_read_b64_tr_b16 v[154:155], v252 offset:19456
	ds_read_b64_tr_b16 v[156:157], v252 offset:17920
	ds_read_b64_tr_b16 v[158:159], v252 offset:19968
	s_waitcnt lgkmcnt(6)
	v_mfma_f32_32x32x16_bf16 v[48:63], v[128:131], v[144:147], v[48:63]
	ds_read_b64_tr_b16 v[144:145], v252 offset:20480
	ds_read_b64_tr_b16 v[146:147], v252 offset:22528
	v_exp_f32_e32 v120, v120
	v_exp_f32_e32 v121, v121
	s_waitcnt lgkmcnt(6)
	v_mfma_f32_32x32x16_bf16 v[32:47], v[128:131], v[148:151], v[32:47]
	ds_read_b64_tr_b16 v[148:149], v252 offset:20992
	ds_read_b64_tr_b16 v[150:151], v252 offset:23040
	v_exp_f32_e32 v122, v122
	v_exp_f32_e32 v123, v123
	v_add_f32_e32 v182, v120, v182
	v_add_f32_e32 v182, v121, v182
	v_cvt_pk_bf16_f32 v132, v120, v121
	s_waitcnt lgkmcnt(6)
	v_mfma_f32_32x32x16_bf16 v[16:31], v[128:131], v[152:155], v[16:31]
	ds_read_b64_tr_b16 v[152:153], v252 offset:21504
	ds_read_b64_tr_b16 v[154:155], v252 offset:23552
	v_exp_f32_e32 v124, v124
	v_exp_f32_e32 v125, v125
	v_add_f32_e32 v182, v122, v182
	v_add_f32_e32 v182, v123, v182
	v_cvt_pk_bf16_f32 v133, v122, v123
	s_waitcnt lgkmcnt(6)
	v_mfma_f32_32x32x16_bf16 v[0:15], v[128:131], v[156:159], v[0:15]
	ds_read_b64_tr_b16 v[156:157], v252 offset:22016
	ds_read_b64_tr_b16 v[158:159], v252 offset:24064
	v_exp_f32_e32 v126, v126
	v_exp_f32_e32 v127, v127
	v_add_f32_e32 v182, v124, v182
	v_add_f32_e32 v182, v125, v182
	v_cvt_pk_bf16_f32 v134, v124, v125
	v_add_f32_e32 v182, v126, v182
	v_add_f32_e32 v182, v127, v182
	v_cvt_pk_bf16_f32 v135, v126, v127
	v_mfma_f32_32x32x16_bf16 v[80:95], v[192:195], v[172:175], v[80:95]
	v_mfma_f32_32x32x16_bf16 v[64:79], v[196:199], v[172:175], v[64:79]
	v_mfma_f32_32x32x16_bf16 v[80:95], v[200:203], v[168:171], v[80:95]
	v_mfma_f32_32x32x16_bf16 v[64:79], v[204:207], v[168:171], v[64:79]
	s_waitcnt lgkmcnt(6)
	v_mfma_f32_32x32x16_bf16 v[48:63], v[132:135], v[144:147], v[48:63]
	ds_read_b64_tr_b16 v[144:145], v252 offset:24576
	ds_read_b64_tr_b16 v[146:147], v252 offset:26624
	v_exp_f32_e32 v96, v96
	v_exp_f32_e32 v97, v97
	s_waitcnt lgkmcnt(6)
	v_mfma_f32_32x32x16_bf16 v[32:47], v[132:135], v[148:151], v[32:47]
	ds_read_b64_tr_b16 v[148:149], v252 offset:25088
	ds_read_b64_tr_b16 v[150:151], v252 offset:27136
	v_exp_f32_e32 v98, v98
	v_exp_f32_e32 v99, v99
	v_add_f32_e32 v182, v96, v182
	v_add_f32_e32 v182, v97, v182
	v_cvt_pk_bf16_f32 v136, v96, v97
	s_waitcnt lgkmcnt(6)
	v_mfma_f32_32x32x16_bf16 v[16:31], v[132:135], v[152:155], v[16:31]
	ds_read_b64_tr_b16 v[152:153], v252 offset:25600
	ds_read_b64_tr_b16 v[154:155], v252 offset:27648
	v_exp_f32_e32 v100, v100
	v_exp_f32_e32 v101, v101
	v_add_f32_e32 v182, v98, v182
	v_add_f32_e32 v182, v99, v182
	v_cvt_pk_bf16_f32 v137, v98, v99
	s_waitcnt lgkmcnt(6)
	v_mfma_f32_32x32x16_bf16 v[0:15], v[132:135], v[156:159], v[0:15]
	ds_read_b64_tr_b16 v[156:157], v252 offset:26112
	ds_read_b64_tr_b16 v[158:159], v252 offset:28160
	v_exp_f32_e32 v102, v102
	v_exp_f32_e32 v103, v103
	v_add_f32_e32 v182, v100, v182
	v_add_f32_e32 v182, v101, v182
	v_cvt_pk_bf16_f32 v138, v100, v101
	v_add_f32_e32 v182, v102, v182
	v_add_f32_e32 v182, v103, v182
	v_cvt_pk_bf16_f32 v139, v102, v103
	v_mfma_f32_32x32x16_bf16 v[80:95], v[208:211], v[164:167], v[80:95]
	v_mfma_f32_32x32x16_bf16 v[64:79], v[212:215], v[164:167], v[64:79]
	v_mfma_f32_32x32x16_bf16 v[80:95], v[216:219], v[160:163], v[80:95]
	v_mfma_f32_32x32x16_bf16 v[64:79], v[220:223], v[160:163], v[64:79]
	s_waitcnt lgkmcnt(6)
	v_mfma_f32_32x32x16_bf16 v[48:63], v[136:139], v[144:147], v[48:63]
	ds_read_b64_tr_b16 v[144:145], v252 offset:28672
	ds_read_b64_tr_b16 v[146:147], v252 offset:30720
	v_exp_f32_e32 v104, v104
	v_exp_f32_e32 v105, v105
	s_waitcnt lgkmcnt(6)
	v_mfma_f32_32x32x16_bf16 v[32:47], v[136:139], v[148:151], v[32:47]
	ds_read_b64_tr_b16 v[148:149], v252 offset:29184
	ds_read_b64_tr_b16 v[150:151], v252 offset:31232
	v_exp_f32_e32 v106, v106
	v_exp_f32_e32 v107, v107
	v_add_f32_e32 v182, v104, v182
	v_add_f32_e32 v182, v105, v182
	v_cvt_pk_bf16_f32 v140, v104, v105
	s_waitcnt lgkmcnt(6)
	v_mfma_f32_32x32x16_bf16 v[16:31], v[136:139], v[152:155], v[16:31]
	ds_read_b64_tr_b16 v[152:153], v252 offset:29696
	ds_read_b64_tr_b16 v[154:155], v252 offset:31744
	v_exp_f32_e32 v108, v108
	v_exp_f32_e32 v109, v109
	v_add_f32_e32 v182, v106, v182
	v_add_f32_e32 v182, v107, v182
	v_cvt_pk_bf16_f32 v141, v106, v107
	s_waitcnt lgkmcnt(6)
	v_mfma_f32_32x32x16_bf16 v[0:15], v[136:139], v[156:159], v[0:15]
	ds_read_b64_tr_b16 v[156:157], v252 offset:30208
	ds_read_b64_tr_b16 v[158:159], v252 offset:32256
	v_exp_f32_e32 v110, v110
	v_exp_f32_e32 v111, v111
	v_add_f32_e32 v182, v108, v182
	v_add_f32_e32 v182, v109, v182
	v_cvt_pk_bf16_f32 v142, v108, v109
	v_add_f32_e32 v182, v110, v182
	v_add_f32_e32 v182, v111, v182
	v_cvt_pk_bf16_f32 v143, v110, v111
	s_nop 1
	s_waitcnt lgkmcnt(6)
	v_mfma_f32_32x32x16_bf16 v[48:63], v[140:143], v[144:147], v[48:63]
	v_exp_f32_e32 v80, v80
	v_exp_f32_e32 v81, v81
	s_waitcnt lgkmcnt(4)
	v_mfma_f32_32x32x16_bf16 v[32:47], v[140:143], v[148:151], v[32:47]
	v_exp_f32_e32 v82, v82
	v_exp_f32_e32 v83, v83
	v_add_f32_e32 v182, v80, v182
	v_add_f32_e32 v182, v81, v182
	v_cvt_pk_bf16_f32 v128, v80, v81
	s_waitcnt lgkmcnt(2)
	v_mfma_f32_32x32x16_bf16 v[16:31], v[140:143], v[152:155], v[16:31]
	v_exp_f32_e32 v84, v84
	v_exp_f32_e32 v85, v85
	v_add_f32_e32 v182, v82, v182
	v_add_f32_e32 v182, v83, v182
	v_cvt_pk_bf16_f32 v129, v82, v83
	s_waitcnt lgkmcnt(0)
	v_mfma_f32_32x32x16_bf16 v[0:15], v[140:143], v[156:159], v[0:15]
	v_exp_f32_e32 v86, v86
	v_exp_f32_e32 v87, v87
	v_add_f32_e32 v182, v84, v182
	v_add_f32_e32 v182, v85, v182
	v_cvt_pk_bf16_f32 v130, v84, v85
	v_add_f32_e32 v182, v86, v182
	v_add_f32_e32 v182, v87, v182
	v_cvt_pk_bf16_f32 v131, v86, v87
	s_nop 1
	s_add_i32 s54, s54, 1
	s_waitcnt vmcnt(0)
	s_barrier
	ds_read_b128 v[192:195], v178 offset:49152
	ds_read_b128 v[196:199], v178 offset:57344
	ds_read_b128 v[200:203], v179 offset:49152
	ds_read_b128 v[204:207], v179 offset:57344
	ds_read_b128 v[208:211], v180 offset:49152
	ds_read_b128 v[212:215], v180 offset:57344
	ds_read_b128 v[216:219], v181 offset:49152
	ds_read_b128 v[220:223], v181 offset:57344
	s_add_i32 s53, s54, 2
	s_cmp_le_i32 s53, s62
	s_cbranch_scc0 .Lsym_nostage_s2
	s_add_u32 s60, s56, 0x70000
	s_addc_u32 s61, s57, 0
	s_add_i32 m0, s25, 0x0
	s_nop 0
	global_load_lds_dwordx4 v176, s[56:57]
	s_add_i32 m0, s25, 0x2000
	s_nop 0
	global_load_lds_dwordx4 v176, s[60:61]
	s_add_i32 m0, s24, 0x0
	s_nop 0
	global_load_lds_dwordx4 v188, s[56:57]
	s_add_i32 m0, s24, 0x2000
	s_nop 0
	global_load_lds_dwordx4 v188, s[60:61]
	s_add_u32 s56, s56, 0xe0000
	s_addc_u32 s57, s57, 0

; template <int KS> __device__ __forceinline__ void pv_ks(f32x16* o, int vb, bf16x8 pa) {
;     const s16x4 l0 = tr_read<v_rd_off(0, KS, 0)>(vb), h0 = tr_read<v_rd_off(0, KS, 1)>(vb), l1 = tr_read<v_rd_off(1, KS, 0)>(vb), h1 = tr_read<v_rd_off(1, KS, 1)>(vb);
;     const s16x4 l2 = tr_read<v_rd_off(2, KS, 0)>(vb), h2 = tr_read<v_rd_off(2, KS, 1)>(vb), l3 = tr_read<v_rd_off(3, KS, 0)>(vb), h3 = tr_read<v_rd_off(3, KS, 1)>(vb);
;     ...
;     asm volatile("s_waitcnt lgkmcnt(6)" ::: "memory"); SBAR();
;     o[0] = __builtin_amdgcn_mfma_f32_32x32x16_bf16(pa, PK(l0, h0), o[0], 0, 0, 0);
;     asm volatile("s_waitcnt lgkmcnt(4)" ::: "memory"); SBAR();
;     o[1] = __builtin_amdgcn_mfma_f32_32x32x16_bf16(pa, PK(l1, h1), o[1], 0, 0, 0);
;     asm volatile("s_waitcnt lgkmcnt(2)" ::: "memory"); SBAR();
;     o[2] = __builtin_amdgcn_mfma_f32_32x32x16_bf16(pa, PK(l2, h2), o[2], 0, 0, 0);
;     asm volatile("s_waitcnt lgkmcnt(0)" ::: "memory"); SBAR();
;     o[3] = __builtin_amdgcn_mfma_f32_32x32x16_bf16(pa, PK(l3, h3), o[3], 0, 0, 0);
;     ...
; }
; __device__ __forceinline__ void pv_d0(f32x16* o, int vb, bf16x8 pa0, bf16x8 pa1, bf16x8 pa2, bf16x8 pa3) {
;     __builtin_amdgcn_s_setprio(1);
;     pv_ks<0>(o, vb, pa0); pv_ks<1>(o, vb, pa1); pv_ks<2>(o, vb, pa2); pv_ks<3>(o, vb, pa3);
;     __builtin_amdgcn_s_setprio(0);
; }
; __device__ __forceinline__ void exp_half(f32x16& p) {
; #pragma unroll
;     for (int r = 0; r < 16; ++r) p[r] = __builtin_amdgcn_exp2f(p[r]);
; }
; __device__ __forceinline__ void pack_p(const f32x16& p0, const f32x16& p1, float& l_reg, bf16x8& pa0, bf16x8& pa1, bf16x8& pa2, bf16x8& pa3) {
;     float ps = 0;
; #pragma unroll
;     for (int r = 0; r < 16; ++r) ps += p0[r];
; #pragma unroll
;     for (int r = 0; r < 16; ++r) ps += p1[r];
;     l_reg += ps;
;     ...
;     PK4(p0, 0, pa0); PK4(p0, 8, pa1); PK4(p1, 0, pa2); PK4(p1, 8, pa3);
;     ...
; }
; template <int ND0> __device__ __forceinline__ void qkt(f32x16& p0, f32x16& p1, const char* Ks, const bf16x8* qr, int r32, int hi, int colB0) {
; #pragma unroll
;     for (int d0 = 0; d0 < ND0; ++d0) { const int cb = colB0 + (d0 * 16 + hi * 8) * 2;
;         const bf16x8 b0 = *reinterpret_cast<const bf16x8*>(Ks + KSWZ(r32, cb));
;         const bf16x8 b1 = *reinterpret_cast<const bf16x8*>(Ks + KSWZ(32 + r32, cb));
;         p0 = __builtin_amdgcn_mfma_f32_32x32x16_bf16(b0, qr[d0], p0, 0, 0, 0);
.Lsym_biasdone_s2:
	ds_read_b64_tr_b16 v[144:145], v252 offset:32768
	ds_read_b64_tr_b16 v[146:147], v252 offset:34816
	ds_read_b64_tr_b16 v[148:149], v252 offset:33280
	ds_read_b64_tr_b16 v[150:151], v252 offset:35328
	ds_read_b64_tr_b16 v[152:153], v252 offset:33792
	ds_read_b64_tr_b16 v[154:155], v252 offset:35840
	ds_read_b64_tr_b16 v[156:157], v252 offset:34304
	ds_read_b64_tr_b16 v[158:159], v252 offset:36352
	s_waitcnt lgkmcnt(6)
	v_mfma_f32_32x32x16_bf16 v[48:63], v[128:131], v[144:147], v[48:63]
	ds_read_b64_tr_b16 v[144:145], v252 offset:36864
	ds_read_b64_tr_b16 v[146:147], v252 offset:38912
	v_exp_f32_e32 v88, v88
	v_exp_f32_e32 v89, v89
	s_waitcnt lgkmcnt(6)
	v_mfma_f32_32x32x16_bf16 v[32:47], v[128:131], v[148:151], v[32:47]
	ds_read_b64_tr_b16 v[148:149], v252 offset:37376
	ds_read_b64_tr_b16 v[150:151], v252 offset:39424
	v_exp_f32_e32 v90, v90
	v_exp_f32_e32 v91, v91
	v_add_f32_e32 v182, v88, v182
	v_add_f32_e32 v182, v89, v182
	v_cvt_pk_bf16_f32 v132, v88, v89
	s_waitcnt lgkmcnt(6)
	v_mfma_f32_32x32x16_bf16 v[16:31], v[128:131], v[152:155], v[16:31]
	ds_read_b64_tr_b16 v[152:153], v252 offset:37888
	ds_read_b64_tr_b16 v[154:155], v252 offset:39936
	v_exp_f32_e32 v92, v92
	v_exp_f32_e32 v93, v93
	v_add_f32_e32 v182, v90, v182
	v_add_f32_e32 v182, v91, v182
	v_cvt_pk_bf16_f32 v133, v90, v91
	s_waitcnt lgkmcnt(6)
	v_mfma_f32_32x32x16_bf16 v[0:15], v[128:131], v[156:159], v[0:15]
	ds_read_b64_tr_b16 v[156:157], v252 offset:38400
	ds_read_b64_tr_b16 v[158:159], v252 offset:40448
	v_exp_f32_e32 v94, v94
	v_exp_f32_e32 v95, v95
	v_add_f32_e32 v182, v92, v182
	v_add_f32_e32 v182, v93, v182
	v_cvt_pk_bf16_f32 v134, v92, v93
	v_add_f32_e32 v182, v94, v182
	v_add_f32_e32 v182, v95, v182
	v_cvt_pk_bf16_f32 v135, v94, v95
	v_mfma_f32_32x32x16_bf16 v[112:127], v[192:195], v[172:175], v[112:127]
	v_mfma_f32_32x32x16_bf16 v[96:111], v[196:199], v[172:175], v[96:111]
	v_mfma_f32_32x32x16_bf16 v[112:127], v[200:203], v[168:171], v[112:127]
	v_mfma_f32_32x32x16_bf16 v[96:111], v[204:207], v[168:171], v[96:111]
	s_waitcnt lgkmcnt(6)
	v_mfma_f32_32x32x16_bf16 v[48:63], v[132:135], v[144:147], v[48:63]
	ds_read_b64_tr_b16 v[144:145], v252 offset:40960
	ds_read_b64_tr_b16 v[146:147], v252 offset:43008
	v_exp_f32_e32 v64, v64
	v_exp_f32_e32 v65, v65
	s_waitcnt lgkmcnt(6)
	v_mfma_f32_32x32x16_bf16 v[32:47], v[132:135], v[148:151], v[32:47]
	ds_read_b64_tr_b16 v[148:149], v252 offset:41472
	ds_read_b64_tr_b16 v[150:151], v252 offset:43520
	v_exp_f32_e32 v66, v66
	v_exp_f32_e32 v67, v67
	v_add_f32_e32 v182, v64, v182
	v_add_f32_e32 v182, v65, v182
	v_cvt_pk_bf16_f32 v136, v64, v65
	s_waitcnt lgkmcnt(6)
	v_mfma_f32_32x32x16_bf16 v[16:31], v[132:135], v[152:155], v[16:31]
	ds_read_b64_tr_b16 v[152:153], v252 offset:41984
	ds_read_b64_tr_b16 v[154:155], v252 offset:44032
	v_exp_f32_e32 v68, v68
	v_exp_f32_e32 v69, v69
	v_add_f32_e32 v182, v66, v182
	v_add_f32_e32 v182, v67, v182
	v_cvt_pk_bf16_f32 v137, v66, v67
	s_waitcnt lgkmcnt(6)
	v_mfma_f32_32x32x16_bf16 v[0:15], v[132:135], v[156:159], v[0:15]
	ds_read_b64_tr_b16 v[156:157], v252 offset:42496
	ds_read_b64_tr_b16 v[158:159], v252 offset:44544
	v_exp_f32_e32 v70, v70
	v_exp_f32_e32 v71, v71
	v_add_f32_e32 v182, v68, v182
	v_add_f32_e32 v182, v69, v182
	v_cvt_pk_bf16_f32 v138, v68, v69
	v_add_f32_e32 v182, v70, v182
	v_add_f32_e32 v182, v71, v182
	v_cvt_pk_bf16_f32 v139, v70, v71
	v_mfma_f32_32x32x16_bf16 v[112:127], v[208:211], v[164:167], v[112:127]
	v_mfma_f32_32x32x16_bf16 v[96:111], v[212:215], v[164:167], v[96:111]
	v_mfma_f32_32x32x16_bf16 v[112:127], v[216:219], v[160:163], v[112:127]
	v_mfma_f32_32x32x16_bf16 v[96:111], v[220:223], v[160:163], v[96:111]
	s_waitcnt lgkmcnt(6)
	v_mfma_f32_32x32x16_bf16 v[48:63], v[136:139], v[144:147], v[48:63]
	ds_read_b64_tr_b16 v[144:145], v252 offset:45056
	ds_read_b64_tr_b16 v[146:147], v252 offset:47104
	v_exp_f32_e32 v72, v72
	v_exp_f32_e32 v73, v73
	s_waitcnt lgkmcnt(6)
	v_mfma_f32_32x32x16_bf16 v[32:47], v[136:139], v[148:151], v[32:47]
	ds_read_b64_tr_b16 v[148:149], v252 offset:45568
	ds_read_b64_tr_b16 v[150:151], v252 offset:47616
	v_exp_f32_e32 v74, v74
	v_exp_f32_e32 v75, v75
	v_add_f32_e32 v182, v72, v182
	v_add_f32_e32 v182, v73, v182
	v_cvt_pk_bf16_f32 v140, v72, v73
	s_waitcnt lgkmcnt(6)
	v_mfma_f32_32x32x16_bf16 v[16:31], v[136:139], v[152:155], v[16:31]
	ds_read_b64_tr_b16 v[152:153], v252 offset:46080
	ds_read_b64_tr_b16 v[154:155], v252 offset:48128
	v_exp_f32_e32 v76, v76
	v_exp_f32_e32 v77, v77
	v_add_f32_e32 v182, v74, v182
	v_add_f32_e32 v182, v75, v182
	v_cvt_pk_bf16_f32 v141, v74, v75
	s_waitcnt lgkmcnt(6)
	v_mfma_f32_32x32x16_bf16 v[0:15], v[136:139], v[156:159], v[0:15]
	ds_read_b64_tr_b16 v[156:157], v252 offset:46592
	ds_read_b64_tr_b16 v[158:159], v252 offset:48640
	v_exp_f32_e32 v78, v78
	v_exp_f32_e32 v79, v79
	v_add_f32_e32 v182, v76, v182
	v_add_f32_e32 v182, v77, v182
	v_cvt_pk_bf16_f32 v142, v76, v77
	v_add_f32_e32 v182, v78, v182
	v_add_f32_e32 v182, v79, v182
	v_cvt_pk_bf16_f32 v143, v78, v79
	s_nop 1
	s_waitcnt lgkmcnt(6)
	v_mfma_f32_32x32x16_bf16 v[48:63], v[140:143], v[144:147], v[48:63]
	v_exp_f32_e32 v112, v112
	v_exp_f32_e32 v113, v113
	s_waitcnt lgkmcnt(4)
	v_mfma_f32_32x32x16_bf16 v[32:47], v[140:143], v[148:151], v[32:47]
	v_exp_f32_e32 v114, v114
	v_exp_f32_e32 v115, v115
	v_add_f32_e32 v182, v112, v182
	v_add_f32_e32 v182, v113, v182
	v_cvt_pk_bf16_f32 v128, v112, v113
	s_waitcnt lgkmcnt(2)
	v_mfma_f32_32x32x16_bf16 v[16:31], v[140:143], v[152:155], v[16:31]
	v_exp_f32_e32 v116, v116
	v_exp_f32_e32 v117, v117
	v_add_f32_e32 v182, v114, v182
	v_add_f32_e32 v182, v115, v182
	v_cvt_pk_bf16_f32 v129, v114, v115
	s_waitcnt lgkmcnt(0)
	v_mfma_f32_32x32x16_bf16 v[0:15], v[140:143], v[156:159], v[0:15]
	v_exp_f32_e32 v118, v118
	v_exp_f32_e32 v119, v119
	v_add_f32_e32 v182, v116, v182
	v_add_f32_e32 v182, v117, v182
	v_cvt_pk_bf16_f32 v130, v116, v117
	v_add_f32_e32 v182, v118, v182
	v_add_f32_e32 v182, v119, v182
	v_cvt_pk_bf16_f32 v131, v118, v119
	s_nop 1
	s_add_i32 s54, s54, 1
	s_cmp_ge_i32 s54, s62
	s_cbranch_scc1 .Lsym_last3
	s_waitcnt vmcnt(0)
	s_barrier
	ds_read_b128 v[192:195], v178 offset:0
	ds_read_b128 v[196:199], v178 offset:8192
	ds_read_b128 v[200:203], v179 offset:0
	ds_read_b128 v[204:207], v179 offset:8192
	ds_read_b128 v[208:211], v180 offset:0
	ds_read_b128 v[212:215], v180 offset:8192
	ds_read_b128 v[216:219], v181 offset:0
	ds_read_b128 v[220:223], v181 offset:8192
	s_add_i32 s53, s54, 2
	s_cmp_le_i32 s53, s62
	s_cbranch_scc0 .Lsym_nostage_s3
	s_add_u32 s60, s56, 0x70000
	s_addc_u32 s61, s57, 0
	s_add_i32 m0, s25, 0x4000
	s_nop 0
	global_load_lds_dwordx4 v176, s[56:57]
	s_add_i32 m0, s25, 0x6000
	s_nop 0
	global_load_lds_dwordx4 v176, s[60:61]
	s_add_i32 m0, s24, 0x4000
	s_nop 0
	global_load_lds_dwordx4 v188, s[56:57]
	s_add_i32 m0, s24, 0x6000
	s_nop 0
	global_load_lds_dwordx4 v188, s[60:61]
	s_add_u32 s56, s56, 0xe0000
	s_addc_u32 s57, s57, 0

; template <int KS> __device__ __forceinline__ void pv_ks(f32x16* o, int vb, bf16x8 pa) {
;     const s16x4 l0 = tr_read<v_rd_off(0, KS, 0)>(vb), h0 = tr_read<v_rd_off(0, KS, 1)>(vb), l1 = tr_read<v_rd_off(1, KS, 0)>(vb), h1 = tr_read<v_rd_off(1, KS, 1)>(vb);
;     const s16x4 l2 = tr_read<v_rd_off(2, KS, 0)>(vb), h2 = tr_read<v_rd_off(2, KS, 1)>(vb), l3 = tr_read<v_rd_off(3, KS, 0)>(vb), h3 = tr_read<v_rd_off(3, KS, 1)>(vb);
;     ...
;     asm volatile("s_waitcnt lgkmcnt(6)" ::: "memory"); SBAR();
;     o[0] = __builtin_amdgcn_mfma_f32_32x32x16_bf16(pa, PK(l0, h0), o[0], 0, 0, 0);
;     asm volatile("s_waitcnt lgkmcnt(4)" ::: "memory"); SBAR();
;     o[1] = __builtin_amdgcn_mfma_f32_32x32x16_bf16(pa, PK(l1, h1), o[1], 0, 0, 0);
;     asm volatile("s_waitcnt lgkmcnt(2)" ::: "memory"); SBAR();
;     o[2] = __builtin_amdgcn_mfma_f32_32x32x16_bf16(pa, PK(l2, h2), o[2], 0, 0, 0);
;     asm volatile("s_waitcnt lgkmcnt(0)" ::: "memory"); SBAR();
;     o[3] = __builtin_amdgcn_mfma_f32_32x32x16_bf16(pa, PK(l3, h3), o[3], 0, 0, 0);
;     ...
; }
; __device__ __forceinline__ void pv_d0(f32x16* o, int vb, bf16x8 pa0, bf16x8 pa1, bf16x8 pa2, bf16x8 pa3) {
;     __builtin_amdgcn_s_setprio(1);
;     pv_ks<0>(o, vb, pa0); pv_ks<1>(o, vb, pa1); pv_ks<2>(o, vb, pa2); pv_ks<3>(o, vb, pa3);
;     __builtin_amdgcn_s_setprio(0);
; }
; __device__ __forceinline__ void exp_half(f32x16& p) {
; #pragma unroll
;     for (int r = 0; r < 16; ++r) p[r] = __builtin_amdgcn_exp2f(p[r]);
; }
; __device__ __forceinline__ void pack_p(const f32x16& p0, const f32x16& p1, float& l_reg, bf16x8& pa0, bf16x8& pa1, bf16x8& pa2, bf16x8& pa3) {
;     float ps = 0;
; #pragma unroll
;     for (int r = 0; r < 16; ++r) ps += p0[r];
; #pragma unroll
;     for (int r = 0; r < 16; ++r) ps += p1[r];
;     l_reg += ps;
;     ...
;     PK4(p0, 0, pa0); PK4(p0, 8, pa1); PK4(p1, 0, pa2); PK4(p1, 8, pa3);
;     ...
; }
; template <int ND0> __device__ __forceinline__ void qkt(f32x16& p0, f32x16& p1, const char* Ks, const bf16x8* qr, int r32, int hi, int colB0) {
; #pragma unroll
;     for (int d0 = 0; d0 < ND0; ++d0) { const int cb = colB0 + (d0 * 16 + hi * 8) * 2;
;         const bf16x8 b0 = *reinterpret_cast<const bf16x8*>(Ks + KSWZ(r32, cb));
;         const bf16x8 b1 = *reinterpret_cast<const bf16x8*>(Ks + KSWZ(32 + r32, cb));
;         p0 = __builtin_amdgcn_mfma_f32_32x32x16_bf16(b0, qr[d0], p0, 0, 0, 0);
.Lsym_biasdone_s3:
	ds_read_b64_tr_b16 v[144:145], v252 offset:49152
	ds_read_b64_tr_b16 v[146:147], v252 offset:51200
	ds_read_b64_tr_b16 v[148:149], v252 offset:49664
	ds_read_b64_tr_b16 v[150:151], v252 offset:51712
	ds_read_b64_tr_b16 v[152:153], v252 offset:50176
	ds_read_b64_tr_b16 v[154:155], v252 offset:52224
	ds_read_b64_tr_b16 v[156:157], v252 offset:50688
	ds_read_b64_tr_b16 v[158:159], v252 offset:52736
	s_waitcnt lgkmcnt(6)
	v_mfma_f32_32x32x16_bf16 v[48:63], v[128:131], v[144:147], v[48:63]
	ds_read_b64_tr_b16 v[144:145], v252 offset:53248
	ds_read_b64_tr_b16 v[146:147], v252 offset:55296
	v_exp_f32_e32 v120, v120
	v_exp_f32_e32 v121, v121
	s_waitcnt lgkmcnt(6)
	v_mfma_f32_32x32x16_bf16 v[32:47], v[128:131], v[148:151], v[32:47]
	ds_read_b64_tr_b16 v[148:149], v252 offset:53760
	ds_read_b64_tr_b16 v[150:151], v252 offset:55808
	v_exp_f32_e32 v122, v122
	v_exp_f32_e32 v123, v123
	v_add_f32_e32 v182, v120, v182
	v_add_f32_e32 v182, v121, v182
	v_cvt_pk_bf16_f32 v132, v120, v121
	s_waitcnt lgkmcnt(6)
	v_mfma_f32_32x32x16_bf16 v[16:31], v[128:131], v[152:155], v[16:31]
	ds_read_b64_tr_b16 v[152:153], v252 offset:54272
	ds_read_b64_tr_b16 v[154:155], v252 offset:56320
	v_exp_f32_e32 v124, v124
	v_exp_f32_e32 v125, v125
	v_add_f32_e32 v182, v122, v182
	v_add_f32_e32 v182, v123, v182
	v_cvt_pk_bf16_f32 v133, v122, v123
	s_waitcnt lgkmcnt(6)
	v_mfma_f32_32x32x16_bf16 v[0:15], v[128:131], v[156:159], v[0:15]
	ds_read_b64_tr_b16 v[156:157], v252 offset:54784
	ds_read_b64_tr_b16 v[158:159], v252 offset:56832
	v_exp_f32_e32 v126, v126
	v_exp_f32_e32 v127, v127
	v_add_f32_e32 v182, v124, v182
	v_add_f32_e32 v182, v125, v182
	v_cvt_pk_bf16_f32 v134, v124, v125
	v_add_f32_e32 v182, v126, v182
	v_add_f32_e32 v182, v127, v182
	v_cvt_pk_bf16_f32 v135, v126, v127
	v_mfma_f32_32x32x16_bf16 v[80:95], v[192:195], v[172:175], v[80:95]
	v_mfma_f32_32x32x16_bf16 v[64:79], v[196:199], v[172:175], v[64:79]
	v_mfma_f32_32x32x16_bf16 v[80:95], v[200:203], v[168:171], v[80:95]
	v_mfma_f32_32x32x16_bf16 v[64:79], v[204:207], v[168:171], v[64:79]
	s_waitcnt lgkmcnt(6)
	v_mfma_f32_32x32x16_bf16 v[48:63], v[132:135], v[144:147], v[48:63]
	ds_read_b64_tr_b16 v[144:145], v252 offset:57344
	ds_read_b64_tr_b16 v[146:147], v252 offset:59392
	v_exp_f32_e32 v96, v96
	v_exp_f32_e32 v97, v97
	s_waitcnt lgkmcnt(6)
	v_mfma_f32_32x32x16_bf16 v[32:47], v[132:135], v[148:151], v[32:47]
	ds_read_b64_tr_b16 v[148:149], v252 offset:57856
	ds_read_b64_tr_b16 v[150:151], v252 offset:59904
	v_exp_f32_e32 v98, v98
	v_exp_f32_e32 v99, v99
	v_add_f32_e32 v182, v96, v182
	v_add_f32_e32 v182, v97, v182
	v_cvt_pk_bf16_f32 v136, v96, v97
	s_waitcnt lgkmcnt(6)
	v_mfma_f32_32x32x16_bf16 v[16:31], v[132:135], v[152:155], v[16:31]
	ds_read_b64_tr_b16 v[152:153], v252 offset:58368
	ds_read_b64_tr_b16 v[154:155], v252 offset:60416
	v_exp_f32_e32 v100, v100
	v_exp_f32_e32 v101, v101
	v_add_f32_e32 v182, v98, v182
	v_add_f32_e32 v182, v99, v182
	v_cvt_pk_bf16_f32 v137, v98, v99
	s_waitcnt lgkmcnt(6)
	v_mfma_f32_32x32x16_bf16 v[0:15], v[132:135], v[156:159], v[0:15]
	ds_read_b64_tr_b16 v[156:157], v252 offset:58880
	ds_read_b64_tr_b16 v[158:159], v252 offset:60928
	v_exp_f32_e32 v102, v102
	v_exp_f32_e32 v103, v103
	v_add_f32_e32 v182, v100, v182
	v_add_f32_e32 v182, v101, v182
	v_cvt_pk_bf16_f32 v138, v100, v101
	v_add_f32_e32 v182, v102, v182
	v_add_f32_e32 v182, v103, v182
	v_cvt_pk_bf16_f32 v139, v102, v103
	v_mfma_f32_32x32x16_bf16 v[80:95], v[208:211], v[164:167], v[80:95]
	v_mfma_f32_32x32x16_bf16 v[64:79], v[212:215], v[164:167], v[64:79]
	v_mfma_f32_32x32x16_bf16 v[80:95], v[216:219], v[160:163], v[80:95]
	v_mfma_f32_32x32x16_bf16 v[64:79], v[220:223], v[160:163], v[64:79]
	s_waitcnt lgkmcnt(6)
	v_mfma_f32_32x32x16_bf16 v[48:63], v[136:139], v[144:147], v[48:63]
	ds_read_b64_tr_b16 v[144:145], v252 offset:61440
	ds_read_b64_tr_b16 v[146:147], v252 offset:63488
	v_exp_f32_e32 v104, v104
	v_exp_f32_e32 v105, v105
	s_waitcnt lgkmcnt(6)
	v_mfma_f32_32x32x16_bf16 v[32:47], v[136:139], v[148:151], v[32:47]
	ds_read_b64_tr_b16 v[148:149], v252 offset:61952
	ds_read_b64_tr_b16 v[150:151], v252 offset:64000
	v_exp_f32_e32 v106, v106
	v_exp_f32_e32 v107, v107
	v_add_f32_e32 v182, v104, v182
	v_add_f32_e32 v182, v105, v182
	v_cvt_pk_bf16_f32 v140, v104, v105
	s_waitcnt lgkmcnt(6)
	v_mfma_f32_32x32x16_bf16 v[16:31], v[136:139], v[152:155], v[16:31]
	ds_read_b64_tr_b16 v[152:153], v252 offset:62464
	ds_read_b64_tr_b16 v[154:155], v252 offset:64512
	v_exp_f32_e32 v108, v108
	v_exp_f32_e32 v109, v109
	v_add_f32_e32 v182, v106, v182
	v_add_f32_e32 v182, v107, v182
	v_cvt_pk_bf16_f32 v141, v106, v107
	s_waitcnt lgkmcnt(6)
	v_mfma_f32_32x32x16_bf16 v[0:15], v[136:139], v[156:159], v[0:15]
	ds_read_b64_tr_b16 v[156:157], v252 offset:62976
	ds_read_b64_tr_b16 v[158:159], v252 offset:65024
	v_exp_f32_e32 v110, v110
	v_exp_f32_e32 v111, v111
	v_add_f32_e32 v182, v108, v182
	v_add_f32_e32 v182, v109, v182
	v_cvt_pk_bf16_f32 v142, v108, v109
	v_add_f32_e32 v182, v110, v182
	v_add_f32_e32 v182, v111, v182
	v_cvt_pk_bf16_f32 v143, v110, v111
	s_nop 1
	s_waitcnt lgkmcnt(6)
	v_mfma_f32_32x32x16_bf16 v[48:63], v[140:143], v[144:147], v[48:63]
	v_exp_f32_e32 v80, v80
	v_exp_f32_e32 v81, v81
	s_waitcnt lgkmcnt(4)
	v_mfma_f32_32x32x16_bf16 v[32:47], v[140:143], v[148:151], v[32:47]
	v_exp_f32_e32 v82, v82
	v_exp_f32_e32 v83, v83
	v_add_f32_e32 v182, v80, v182
	v_add_f32_e32 v182, v81, v182
	v_cvt_pk_bf16_f32 v128, v80, v81
	s_waitcnt lgkmcnt(2)
	v_mfma_f32_32x32x16_bf16 v[16:31], v[140:143], v[152:155], v[16:31]
	v_exp_f32_e32 v84, v84
	v_exp_f32_e32 v85, v85
	v_add_f32_e32 v182, v82, v182
	v_add_f32_e32 v182, v83, v182
	v_cvt_pk_bf16_f32 v129, v82, v83
	s_waitcnt lgkmcnt(0)
	v_mfma_f32_32x32x16_bf16 v[0:15], v[140:143], v[156:159], v[0:15]
	v_exp_f32_e32 v86, v86
	v_exp_f32_e32 v87, v87
	v_add_f32_e32 v182, v84, v182
	v_add_f32_e32 v182, v85, v182
	v_cvt_pk_bf16_f32 v130, v84, v85
	v_add_f32_e32 v182, v86, v182
	v_add_f32_e32 v182, v87, v182
	v_cvt_pk_bf16_f32 v131, v86, v87
	s_nop 1
	s_add_i32 s54, s54, 1
	s_branch .Lsym_loop
; template <int KS> __device__ __forceinline__ void pv_ks(f32x16* o, int vb, bf16x8 pa) {
;     const s16x4 l0 = tr_read<v_rd_off(0, KS, 0)>(vb), h0 = tr_read<v_rd_off(0, KS, 1)>(vb), l1 = tr_read<v_rd_off(1, KS, 0)>(vb), h1 = tr_read<v_rd_off(1, KS, 1)>(vb);
;     const s16x4 l2 = tr_read<v_rd_off(2, KS, 0)>(vb), h2 = tr_read<v_rd_off(2, KS, 1)>(vb), l3 = tr_read<v_rd_off(3, KS, 0)>(vb), h3 = tr_read<v_rd_off(3, KS, 1)>(vb);
;     ...
;     asm volatile("s_waitcnt lgkmcnt(6)" ::: "memory"); SBAR();
;     o[0] = __builtin_amdgcn_mfma_f32_32x32x16_bf16(pa, PK(l0, h0), o[0], 0, 0, 0);
;     asm volatile("s_waitcnt lgkmcnt(4)" ::: "memory"); SBAR();
;     o[1] = __builtin_amdgcn_mfma_f32_32x32x16_bf16(pa, PK(l1, h1), o[1], 0, 0, 0);
;     asm volatile("s_waitcnt lgkmcnt(2)" ::: "memory"); SBAR();
;     o[2] = __builtin_amdgcn_mfma_f32_32x32x16_bf16(pa, PK(l2, h2), o[2], 0, 0, 0);
;     asm volatile("s_waitcnt lgkmcnt(0)" ::: "memory"); SBAR();
;     o[3] = __builtin_amdgcn_mfma_f32_32x32x16_bf16(pa, PK(l3, h3), o[3], 0, 0, 0);
;     ...
; }
; __device__ __forceinline__ void pv_d0(f32x16* o, int vb, bf16x8 pa0, bf16x8 pa1, bf16x8 pa2, bf16x8 pa3) {
;     __builtin_amdgcn_s_setprio(1);
;     pv_ks<0>(o, vb, pa0); pv_ks<1>(o, vb, pa1); pv_ks<2>(o, vb, pa2); pv_ks<3>(o, vb, pa3);
;     __builtin_amdgcn_s_setprio(0);
; }
; __device__ __forceinline__ void exp_half(f32x16& p) {
; #pragma unroll
;     for (int r = 0; r < 16; ++r) p[r] = __builtin_amdgcn_exp2f(p[r]);
; }
; __device__ __forceinline__ void pack_p(const f32x16& p0, const f32x16& p1, float& l_reg, bf16x8& pa0, bf16x8& pa1, bf16x8& pa2, bf16x8& pa3) {
;     float ps = 0;
; #pragma unroll
;     for (int r = 0; r < 16; ++r) ps += p0[r];
; #pragma unroll
;     for (int r = 0; r < 16; ++r) ps += p1[r];
;     l_reg += ps;
;     ...
;     PK4(p0, 0, pa0); PK4(p0, 8, pa1); PK4(p1, 0, pa2); PK4(p1, 8, pa3);
;     ...
; }
; __device__ __forceinline__ void diff_unit(const DiffArgs& A, int b, int h, int qb, char* lds, int wv) {
;     ...
;         { const int lt_ = opaque_tid(wv) & 63;
;           SBAR(); BIAS(pB0, pB1, NT - 1); qkt<4>(pB0, pB1, K_lds + SLOT(NT - 1), qr, lt_ & 31, lt_ >> 5, colB0); }
;         exp_half(pA1); pack_p(pA0, pA1, l_reg, pa0, pa1, pa2, pa3); SBAR();
;         pv_d0(o, vb0 + SLOT(NT - 2), pa0, pa1, pa2, pa3); exp_half(pB0);
;         exp_half(pB1); pack_p(pB0, pB1, l_reg, pa0, pa1, pa2, pa3); SBAR();
.Lsym_last1:
	s_waitcnt vmcnt(0)
	s_barrier
	ds_read_b64_tr_b16 v[144:145], v252 offset:16384
	ds_read_b64_tr_b16 v[146:147], v252 offset:18432
	ds_read_b64_tr_b16 v[148:149], v252 offset:16896
	ds_read_b64_tr_b16 v[150:151], v252 offset:18944
	ds_read_b64_tr_b16 v[152:153], v252 offset:17408
	ds_read_b64_tr_b16 v[154:155], v252 offset:19456
	ds_read_b64_tr_b16 v[156:157], v252 offset:17920
	ds_read_b64_tr_b16 v[158:159], v252 offset:19968
	s_waitcnt lgkmcnt(6)
	v_mfma_f32_32x32x16_bf16 v[48:63], v[128:131], v[144:147], v[48:63]
	ds_read_b64_tr_b16 v[144:145], v252 offset:20480
	ds_read_b64_tr_b16 v[146:147], v252 offset:22528
	v_exp_f32_e32 v120, v120
	v_exp_f32_e32 v121, v121
	s_waitcnt lgkmcnt(6)
	v_mfma_f32_32x32x16_bf16 v[32:47], v[128:131], v[148:151], v[32:47]
	ds_read_b64_tr_b16 v[148:149], v252 offset:20992
	ds_read_b64_tr_b16 v[150:151], v252 offset:23040
	v_exp_f32_e32 v122, v122
	v_exp_f32_e32 v123, v123
	v_add_f32_e32 v182, v120, v182
	v_add_f32_e32 v182, v121, v182
	v_cvt_pk_bf16_f32 v132, v120, v121
	s_waitcnt lgkmcnt(6)
	v_mfma_f32_32x32x16_bf16 v[16:31], v[128:131], v[152:155], v[16:31]
	ds_read_b64_tr_b16 v[152:153], v252 offset:21504
	ds_read_b64_tr_b16 v[154:155], v252 offset:23552
	v_exp_f32_e32 v124, v124
	v_exp_f32_e32 v125, v125
	v_add_f32_e32 v182, v122, v182
	v_add_f32_e32 v182, v123, v182
	v_cvt_pk_bf16_f32 v133, v122, v123
	s_waitcnt lgkmcnt(6)
	v_mfma_f32_32x32x16_bf16 v[0:15], v[128:131], v[156:159], v[0:15]
	ds_read_b64_tr_b16 v[156:157], v252 offset:22016
	ds_read_b64_tr_b16 v[158:159], v252 offset:24064
	v_exp_f32_e32 v126, v126
	v_exp_f32_e32 v127, v127
	v_add_f32_e32 v182, v124, v182
	v_add_f32_e32 v182, v125, v182
	v_cvt_pk_bf16_f32 v134, v124, v125
	v_add_f32_e32 v182, v126, v182
	v_add_f32_e32 v182, v127, v182
	v_cvt_pk_bf16_f32 v135, v126, v127
	s_nop 1
	s_waitcnt lgkmcnt(6)
	v_mfma_f32_32x32x16_bf16 v[48:63], v[132:135], v[144:147], v[48:63]
	ds_read_b64_tr_b16 v[144:145], v252 offset:24576
	ds_read_b64_tr_b16 v[146:147], v252 offset:26624
	v_exp_f32_e32 v96, v96
	v_exp_f32_e32 v97, v97
	s_waitcnt lgkmcnt(6)
	v_mfma_f32_32x32x16_bf16 v[32:47], v[132:135], v[148:151], v[32:47]
	ds_read_b64_tr_b16 v[148:149], v252 offset:25088
	ds_read_b64_tr_b16 v[150:151], v252 offset:27136
	v_exp_f32_e32 v98, v98
	v_exp_f32_e32 v99, v99
	v_add_f32_e32 v182, v96, v182
	v_add_f32_e32 v182, v97, v182
	v_cvt_pk_bf16_f32 v136, v96, v97
	s_waitcnt lgkmcnt(6)
	v_mfma_f32_32x32x16_bf16 v[16:31], v[132:135], v[152:155], v[16:31]
	ds_read_b64_tr_b16 v[152:153], v252 offset:25600
	ds_read_b64_tr_b16 v[154:155], v252 offset:27648
	v_exp_f32_e32 v100, v100
	v_exp_f32_e32 v101, v101
	v_add_f32_e32 v182, v98, v182
	v_add_f32_e32 v182, v99, v182
	v_cvt_pk_bf16_f32 v137, v98, v99
	s_waitcnt lgkmcnt(6)
	v_mfma_f32_32x32x16_bf16 v[0:15], v[132:135], v[156:159], v[0:15]
	ds_read_b64_tr_b16 v[156:157], v252 offset:26112
	ds_read_b64_tr_b16 v[158:159], v252 offset:28160
	v_exp_f32_e32 v102, v102
	v_exp_f32_e32 v103, v103
	v_add_f32_e32 v182, v100, v182
	v_add_f32_e32 v182, v101, v182
	v_cvt_pk_bf16_f32 v138, v100, v101
	v_add_f32_e32 v182, v102, v182
	v_add_f32_e32 v182, v103, v182
	v_cvt_pk_bf16_f32 v139, v102, v103
	s_nop 1
	s_waitcnt lgkmcnt(6)
	v_mfma_f32_32x32x16_bf16 v[48:63], v[136:139], v[144:147], v[48:63]
	ds_read_b64_tr_b16 v[144:145], v252 offset:28672
	ds_read_b64_tr_b16 v[146:147], v252 offset:30720
	v_exp_f32_e32 v104, v104
	v_exp_f32_e32 v105, v105
	s_waitcnt lgkmcnt(6)
	v_mfma_f32_32x32x16_bf16 v[32:47], v[136:139], v[148:151], v[32:47]
	ds_read_b64_tr_b16 v[148:149], v252 offset:29184
	ds_read_b64_tr_b16 v[150:151], v252 offset:31232
	v_exp_f32_e32 v106, v106
	v_exp_f32_e32 v107, v107
	v_add_f32_e32 v182, v104, v182
	v_add_f32_e32 v182, v105, v182
	v_cvt_pk_bf16_f32 v140, v104, v105
	s_waitcnt lgkmcnt(6)
	v_mfma_f32_32x32x16_bf16 v[16:31], v[136:139], v[152:155], v[16:31]
	ds_read_b64_tr_b16 v[152:153], v252 offset:29696
	ds_read_b64_tr_b16 v[154:155], v252 offset:31744
	v_exp_f32_e32 v108, v108
	v_exp_f32_e32 v109, v109
	v_add_f32_e32 v182, v106, v182
	v_add_f32_e32 v182, v107, v182
	v_cvt_pk_bf16_f32 v141, v106, v107
	s_waitcnt lgkmcnt(6)
	v_mfma_f32_32x32x16_bf16 v[0:15], v[136:139], v[156:159], v[0:15]
	ds_read_b64_tr_b16 v[156:157], v252 offset:30208
	ds_read_b64_tr_b16 v[158:159], v252 offset:32256
	v_exp_f32_e32 v110, v110
	v_exp_f32_e32 v111, v111
	v_add_f32_e32 v182, v108, v182
	v_add_f32_e32 v182, v109, v182
	v_cvt_pk_bf16_f32 v142, v108, v109
	v_add_f32_e32 v182, v110, v182
	v_add_f32_e32 v182, v111, v182
	v_cvt_pk_bf16_f32 v143, v110, v111
	s_nop 1
	s_waitcnt lgkmcnt(6)
	v_mfma_f32_32x32x16_bf16 v[48:63], v[140:143], v[144:147], v[48:63]
	s_waitcnt lgkmcnt(4)
	v_mfma_f32_32x32x16_bf16 v[32:47], v[140:143], v[148:151], v[32:47]
	s_waitcnt lgkmcnt(2)
	v_mfma_f32_32x32x16_bf16 v[16:31], v[140:143], v[152:155], v[16:31]
	s_waitcnt lgkmcnt(0)
	v_mfma_f32_32x32x16_bf16 v[0:15], v[140:143], v[156:159], v[0:15]
	s_branch .Lsym_done
; template <int KS> __device__ __forceinline__ void pv_ks(f32x16* o, int vb, bf16x8 pa) {
;     const s16x4 l0 = tr_read<v_rd_off(0, KS, 0)>(vb), h0 = tr_read<v_rd_off(0, KS, 1)>(vb), l1 = tr_read<v_rd_off(1, KS, 0)>(vb), h1 = tr_read<v_rd_off(1, KS, 1)>(vb);
;     const s16x4 l2 = tr_read<v_rd_off(2, KS, 0)>(vb), h2 = tr_read<v_rd_off(2, KS, 1)>(vb), l3 = tr_read<v_rd_off(3, KS, 0)>(vb), h3 = tr_read<v_rd_off(3, KS, 1)>(vb);
;     ...
;     asm volatile("s_waitcnt lgkmcnt(6)" ::: "memory"); SBAR();
;     o[0] = __builtin_amdgcn_mfma_f32_32x32x16_bf16(pa, PK(l0, h0), o[0], 0, 0, 0);
;     asm volatile("s_waitcnt lgkmcnt(4)" ::: "memory"); SBAR();
;     o[1] = __builtin_amdgcn_mfma_f32_32x32x16_bf16(pa, PK(l1, h1), o[1], 0, 0, 0);
;     asm volatile("s_waitcnt lgkmcnt(2)" ::: "memory"); SBAR();
;     o[2] = __builtin_amdgcn_mfma_f32_32x32x16_bf16(pa, PK(l2, h2), o[2], 0, 0, 0);
;     asm volatile("s_waitcnt lgkmcnt(0)" ::: "memory"); SBAR();
;     o[3] = __builtin_amdgcn_mfma_f32_32x32x16_bf16(pa, PK(l3, h3), o[3], 0, 0, 0);
;     ...
; }
; __device__ __forceinline__ void pv_d0(f32x16* o, int vb, bf16x8 pa0, bf16x8 pa1, bf16x8 pa2, bf16x8 pa3) {
;     __builtin_amdgcn_s_setprio(1);
;     pv_ks<0>(o, vb, pa0); pv_ks<1>(o, vb, pa1); pv_ks<2>(o, vb, pa2); pv_ks<3>(o, vb, pa3);
;     __builtin_amdgcn_s_setprio(0);
; }
; __device__ __forceinline__ void exp_half(f32x16& p) {
; #pragma unroll
;     for (int r = 0; r < 16; ++r) p[r] = __builtin_amdgcn_exp2f(p[r]);
; }
; __device__ __forceinline__ void pack_p(const f32x16& p0, const f32x16& p1, float& l_reg, bf16x8& pa0, bf16x8& pa1, bf16x8& pa2, bf16x8& pa3) {
;     float ps = 0;
; #pragma unroll
;     for (int r = 0; r < 16; ++r) ps += p0[r];
; #pragma unroll
;     for (int r = 0; r < 16; ++r) ps += p1[r];
;     l_reg += ps;
;     ...
;     PK4(p0, 0, pa0); PK4(p0, 8, pa1); PK4(p1, 0, pa2); PK4(p1, 8, pa3);
;     ...
; }
; __device__ __forceinline__ void diff_unit(const DiffArgs& A, int b, int h, int qb, char* lds, int wv) {
;     ...
;         { const int lt_ = opaque_tid(wv) & 63;
;           SBAR(); BIAS(pB0, pB1, NT - 1); qkt<4>(pB0, pB1, K_lds + SLOT(NT - 1), qr, lt_ & 31, lt_ >> 5, colB0); }
;         exp_half(pA1); pack_p(pA0, pA1, l_reg, pa0, pa1, pa2, pa3); SBAR();
;         pv_d0(o, vb0 + SLOT(NT - 2), pa0, pa1, pa2, pa3); exp_half(pB0);
;         exp_half(pB1); pack_p(pB0, pB1, l_reg, pa0, pa1, pa2, pa3); SBAR();
.Lsym_last3:
	s_waitcnt vmcnt(0)
	s_barrier
	ds_read_b64_tr_b16 v[144:145], v252 offset:49152
	ds_read_b64_tr_b16 v[146:147], v252 offset:51200
	ds_read_b64_tr_b16 v[148:149], v252 offset:49664
	ds_read_b64_tr_b16 v[150:151], v252 offset:51712
	ds_read_b64_tr_b16 v[152:153], v252 offset:50176
	ds_read_b64_tr_b16 v[154:155], v252 offset:52224
	ds_read_b64_tr_b16 v[156:157], v252 offset:50688
	ds_read_b64_tr_b16 v[158:159], v252 offset:52736
	s_waitcnt lgkmcnt(6)
	v_mfma_f32_32x32x16_bf16 v[48:63], v[128:131], v[144:147], v[48:63]
	ds_read_b64_tr_b16 v[144:145], v252 offset:53248
	ds_read_b64_tr_b16 v[146:147], v252 offset:55296
	v_exp_f32_e32 v120, v120
	v_exp_f32_e32 v121, v121
	s_waitcnt lgkmcnt(6)
	v_mfma_f32_32x32x16_bf16 v[32:47], v[128:131], v[148:151], v[32:47]
	ds_read_b64_tr_b16 v[148:149], v252 offset:53760
	ds_read_b64_tr_b16 v[150:151], v252 offset:55808
	v_exp_f32_e32 v122, v122
	v_exp_f32_e32 v123, v123
	v_add_f32_e32 v182, v120, v182
	v_add_f32_e32 v182, v121, v182
	v_cvt_pk_bf16_f32 v132, v120, v121
	s_waitcnt lgkmcnt(6)
	v_mfma_f32_32x32x16_bf16 v[16:31], v[128:131], v[152:155], v[16:31]
	ds_read_b64_tr_b16 v[152:153], v252 offset:54272
	ds_read_b64_tr_b16 v[154:155], v252 offset:56320
	v_exp_f32_e32 v124, v124
	v_exp_f32_e32 v125, v125
	v_add_f32_e32 v182, v122, v182
	v_add_f32_e32 v182, v123, v182
	v_cvt_pk_bf16_f32 v133, v122, v123
	s_waitcnt lgkmcnt(6)
	v_mfma_f32_32x32x16_bf16 v[0:15], v[128:131], v[156:159], v[0:15]
	ds_read_b64_tr_b16 v[156:157], v252 offset:54784
	ds_read_b64_tr_b16 v[158:159], v252 offset:56832
	v_exp_f32_e32 v126, v126
	v_exp_f32_e32 v127, v127
	v_add_f32_e32 v182, v124, v182
	v_add_f32_e32 v182, v125, v182
	v_cvt_pk_bf16_f32 v134, v124, v125
	v_add_f32_e32 v182, v126, v182
	v_add_f32_e32 v182, v127, v182
	v_cvt_pk_bf16_f32 v135, v126, v127
	s_nop 1
	s_waitcnt lgkmcnt(6)
	v_mfma_f32_32x32x16_bf16 v[48:63], v[132:135], v[144:147], v[48:63]
	ds_read_b64_tr_b16 v[144:145], v252 offset:57344
	ds_read_b64_tr_b16 v[146:147], v252 offset:59392
	v_exp_f32_e32 v96, v96
	v_exp_f32_e32 v97, v97
	s_waitcnt lgkmcnt(6)
	v_mfma_f32_32x32x16_bf16 v[32:47], v[132:135], v[148:151], v[32:47]
	ds_read_b64_tr_b16 v[148:149], v252 offset:57856
	ds_read_b64_tr_b16 v[150:151], v252 offset:59904
	v_exp_f32_e32 v98, v98
	v_exp_f32_e32 v99, v99
	v_add_f32_e32 v182, v96, v182
	v_add_f32_e32 v182, v97, v182
	v_cvt_pk_bf16_f32 v136, v96, v97
	s_waitcnt lgkmcnt(6)
	v_mfma_f32_32x32x16_bf16 v[16:31], v[132:135], v[152:155], v[16:31]
	ds_read_b64_tr_b16 v[152:153], v252 offset:58368
	ds_read_b64_tr_b16 v[154:155], v252 offset:60416
	v_exp_f32_e32 v100, v100
	v_exp_f32_e32 v101, v101
	v_add_f32_e32 v182, v98, v182
	v_add_f32_e32 v182, v99, v182
	v_cvt_pk_bf16_f32 v137, v98, v99
	s_waitcnt lgkmcnt(6)
	v_mfma_f32_32x32x16_bf16 v[0:15], v[132:135], v[156:159], v[0:15]
	ds_read_b64_tr_b16 v[156:157], v252 offset:58880
	ds_read_b64_tr_b16 v[158:159], v252 offset:60928
	v_exp_f32_e32 v102, v102
	v_exp_f32_e32 v103, v103
	v_add_f32_e32 v182, v100, v182
	v_add_f32_e32 v182, v101, v182
	v_cvt_pk_bf16_f32 v138, v100, v101
	v_add_f32_e32 v182, v102, v182
	v_add_f32_e32 v182, v103, v182
	v_cvt_pk_bf16_f32 v139, v102, v103
	s_nop 1
	s_waitcnt lgkmcnt(6)
	v_mfma_f32_32x32x16_bf16 v[48:63], v[136:139], v[144:147], v[48:63]
	ds_read_b64_tr_b16 v[144:145], v252 offset:61440
	ds_read_b64_tr_b16 v[146:147], v252 offset:63488
	v_exp_f32_e32 v104, v104
	v_exp_f32_e32 v105, v105
	s_waitcnt lgkmcnt(6)
	v_mfma_f32_32x32x16_bf16 v[32:47], v[136:139], v[148:151], v[32:47]
	ds_read_b64_tr_b16 v[148:149], v252 offset:61952
	ds_read_b64_tr_b16 v[150:151], v252 offset:64000
	v_exp_f32_e32 v106, v106
	v_exp_f32_e32 v107, v107
	v_add_f32_e32 v182, v104, v182
	v_add_f32_e32 v182, v105, v182
	v_cvt_pk_bf16_f32 v140, v104, v105
	s_waitcnt lgkmcnt(6)
	v_mfma_f32_32x32x16_bf16 v[16:31], v[136:139], v[152:155], v[16:31]
	ds_read_b64_tr_b16 v[152:153], v252 offset:62464
	ds_read_b64_tr_b16 v[154:155], v252 offset:64512
	v_exp_f32_e32 v108, v108
	v_exp_f32_e32 v109, v109
	v_add_f32_e32 v182, v106, v182
	v_add_f32_e32 v182, v107, v182
	v_cvt_pk_bf16_f32 v141, v106, v107
	s_waitcnt lgkmcnt(6)
	v_mfma_f32_32x32x16_bf16 v[0:15], v[136:139], v[156:159], v[0:15]
	ds_read_b64_tr_b16 v[156:157], v252 offset:62976
	ds_read_b64_tr_b16 v[158:159], v252 offset:65024
	v_exp_f32_e32 v110, v110
	v_exp_f32_e32 v111, v111
	v_add_f32_e32 v182, v108, v182
	v_add_f32_e32 v182, v109, v182
	v_cvt_pk_bf16_f32 v142, v108, v109
	v_add_f32_e32 v182, v110, v182
	v_add_f32_e32 v182, v111, v182
	v_cvt_pk_bf16_f32 v143, v110, v111
	s_nop 1
	s_waitcnt lgkmcnt(6)
	v_mfma_f32_32x32x16_bf16 v[48:63], v[140:143], v[144:147], v[48:63]
	s_waitcnt lgkmcnt(4)
	v_mfma_f32_32x32x16_bf16 v[32:47], v[140:143], v[148:151], v[32:47]
	s_waitcnt lgkmcnt(2)
	v_mfma_f32_32x32x16_bf16 v[16:31], v[140:143], v[152:155], v[16:31]
	s_waitcnt lgkmcnt(0)
	v_mfma_f32_32x32x16_bf16 v[0:15], v[140:143], v[156:159], v[0:15]
